# one static s_setprio 1 for waves 4-7 from the first GEMM phase on (no per-segment flips)
# speedup vs baseline: 1.0079x; 1.0030x over previous
; template <class Epi, class Sched, bool ALIGN_EPI = false, bool SP2 = false>
; __device__ __forceinline__ void gemm_phase(PG8_LAS unsigned char* lds, const Gemm g, const Sched& S, const Epi& E) {
;     const int tid = threadIdx.x, wid = __builtin_amdgcn_readfirstlane(tid >> 6), lane = tid & 63, wr = wid >> 2, wc = wid & 3, fr = lane & 15, fq = lane >> 4;
.LBB0_196:
	v_readlane_b32 s98, v249, 18
	s_nop 3
	s_cmp_ge_u32 s98, 4
	s_cbranch_scc0 .Lprio_done
	s_setprio 1
